# k20 + hyena_ctx_item: six neighbour-token ushort loads no longer waited one by one (loaded into their final registers, shifts after the common vmcnt(0) join)
# speedup vs baseline: 1.0063x; 1.0063x over previous
.LBB0_1425:
	v_mov_b32_e32 v2, v0
	s_mul_i32 s0, s14, 0x4400
	s_mul_hi_i32 s1, s14, 0x4400
	v_and_b32_e32 v4, 0xffffff00, v2
	s_add_u32 s0, s11, s0
	v_ashrrev_i32_e32 v5, 31, v4
	s_addc_u32 s1, s10, s1
	v_and_b32_e32 v36, 0xff, v2
	v_lshl_add_u64 v[6:7], v[4:5], 1, s[0:1]
	v_cmp_ne_u32_e32 vcc, 0, v36
	v_lshl_add_u64 v[6:7], v[6:7], 0, s[6:7]
	v_lshlrev_b32_e32 v10, 1, v36
	v_mov_b32_e32 v37, 0
	s_and_saveexec_b64 s[0:1], vcc
	s_cbranch_execz .LBB0_1427
	v_lshl_add_u64 v[8:9], v[6:7], 0, v[10:11]
	global_load_ushort v37, v[8:9], off offset:-2
.LBB0_1427:
	s_or_b64 exec, exec, s[0:1]
	v_lshl_add_u64 v[6:7], v[6:7], 0, v[10:11]
	global_load_ushort v38, v[6:7], off
	v_cmp_ne_u32_e64 s[0:1], s3, v36
	v_mov_b32_e32 v18, 0
	v_mov_b32_e32 v39, 0
	s_and_saveexec_b64 s[4:5], s[0:1]
	s_cbranch_execz .LBB0_1429
	global_load_ushort v39, v[6:7], off offset:2
.LBB0_1429:
	s_or_b64 exec, exec, s[4:5]
	s_ashr_i32 s15, s14, 31
	s_lshl_b64 s[16:17], s[14:15], 2
	s_add_u32 s4, s95, s16
	s_addc_u32 s5, s94, s17
	s_add_u32 s18, s97, s16
	s_addc_u32 s19, s96, s17
	global_load_dword v40, v11, s[4:5]
	global_load_dword v42, v1, s[4:5]
	global_load_dword v41, v11, s[18:19]
	global_load_dword v43, v22, s[4:5]
	s_add_i32 s28, s14, 0x400
	s_mul_i32 s20, s28, 0x4400
	s_mul_hi_i32 s21, s28, 0x4400
	s_add_u32 s20, s11, s20
	s_addc_u32 s21, s10, s21
	v_lshl_add_u64 v[6:7], v[4:5], 1, s[20:21]
	v_lshl_add_u64 v[6:7], v[6:7], 0, s[6:7]
	s_and_saveexec_b64 s[20:21], vcc
	s_cbranch_execz .LBB0_1431
	v_lshl_add_u64 v[8:9], v[6:7], 0, v[10:11]
	global_load_ushort v18, v[8:9], off offset:-2
.LBB0_1431:
	s_or_b64 exec, exec, s[20:21]
	v_lshl_add_u64 v[6:7], v[6:7], 0, v[10:11]
	global_load_ushort v20, v[6:7], off
	v_mov_b32_e32 v12, 0
	v_mov_b32_e32 v19, 0
	s_and_saveexec_b64 s[20:21], s[0:1]
	s_cbranch_execz .LBB0_1433
	global_load_ushort v19, v[6:7], off offset:2
.LBB0_1433:
	s_or_b64 exec, exec, s[20:21]
	global_load_dword v35, v24, s[4:5]
	global_load_dword v21, v25, s[4:5]
	global_load_dword v34, v23, s[4:5]
	global_load_dword v33, v23, s[18:19]
	s_add_i32 s20, s14, 0x800
	s_mul_i32 s22, s20, 0x4400
	s_mul_hi_i32 s21, s20, 0x4400
	s_add_u32 s22, s11, s22
	s_addc_u32 s23, s10, s21
	v_lshl_add_u64 v[6:7], v[4:5], 1, s[22:23]
	v_lshl_add_u64 v[6:7], v[6:7], 0, s[6:7]
	s_and_saveexec_b64 s[22:23], vcc
	s_cbranch_execz .LBB0_1435
	v_lshl_add_u64 v[8:9], v[6:7], 0, v[10:11]
	global_load_ushort v12, v[8:9], off offset:-2
.LBB0_1435:
	s_or_b64 exec, exec, s[22:23]
	v_lshl_add_u64 v[6:7], v[6:7], 0, v[10:11]
	global_load_ushort v31, v[6:7], off
	v_mov_b32_e32 v5, 0
	v_mov_b32_e32 v13, 0
	s_and_saveexec_b64 s[22:23], s[0:1]
	s_cbranch_execz .LBB0_1437
	global_load_ushort v13, v[6:7], off offset:2

.LBB0_1445:
	s_or_b64 exec, exec, s[0:1]
	v_add3_u32 v16, v4, v36, s26
	v_mov_b64_e32 v[6:7], s[38:39]
	v_mad_i64_i32 v[6:7], s[0:1], v16, s27, v[6:7]
	v_lshl_add_u64 v[6:7], s[14:15], 1, v[6:7]
	v_add_co_u32_e32 v6, vcc, 0x2000, v6
	s_waitcnt vmcnt(0)
	v_lshlrev_b32_e32 v37, 16, v37
	v_lshlrev_b32_e32 v39, 16, v39
	v_lshlrev_b32_e32 v18, 16, v18
	v_lshlrev_b32_e32 v19, 16, v19
	v_lshlrev_b32_e32 v12, 16, v12
	v_lshlrev_b32_e32 v13, 16, v13
	v_and_b32_e32 v3, 0x7fffffff, v5
	v_addc_co_u32_e32 v7, vcc, 0, v7, vcc
	global_load_ushort v32, v[6:7], off offset:2048
	ds_bpermute_b32 v3, v132, v3
	v_and_b32_e32 v6, 63, v2
	v_cmp_eq_u32_e32 vcc, 0, v6
	v_ashrrev_i32_e32 v6, 4, v2
	v_add_u32_e32 v47, 0, v6
	s_waitcnt lgkmcnt(0)
	v_add_f32_e64 v3, |v5|, v3
	ds_bpermute_b32 v4, v133, v3
	s_waitcnt lgkmcnt(0)
	s_barrier
	v_add_f32_e32 v3, v3, v4
	ds_bpermute_b32 v4, v134, v3
	s_waitcnt lgkmcnt(0)
	v_add_f32_e32 v3, v3, v4
	ds_bpermute_b32 v4, v135, v3
	s_waitcnt lgkmcnt(0)
	v_add_f32_e32 v3, v3, v4
	ds_bpermute_b32 v4, v136, v3
	s_waitcnt lgkmcnt(0)
	v_add_f32_e32 v3, v3, v4
	ds_bpermute_b32 v4, v137, v3
	s_and_saveexec_b64 s[0:1], vcc
	s_cbranch_execz .LBB0_1447
	s_waitcnt lgkmcnt(0)
	v_add_f32_e32 v3, v3, v4
	ds_write_b32 v47, v3 offset:4096
